# norm rows loop: non-temporal hint on the streamed f32 x-row loads (same arithmetic)
# speedup vs baseline: 1.0184x; 1.0164x over previous
.LBB0_180:
	v_readlane_b32 s0, v253, 39
	s_movk_i32 s3, 0x4000
	v_add_u32_e32 v0, 0xffffc000, v50
	v_mov_b32_e32 v34, s0
	v_readlane_b32 s0, v253, 37
	v_cmp_gt_i32_e32 vcc, s3, v50
	v_min_i32_e32 v12, 0x4000, v50
	v_mov_b32_e32 v35, s0
	v_readlane_b32 s0, v253, 40
	v_cndmask_b32_e32 v3, 0, v51, vcc
	v_cndmask_b32_e32 v2, v0, v50, vcc
	v_mov_b32_e32 v36, s0
	v_readlane_b32 s0, v253, 38
	v_cndmask_b32_e32 v5, v34, v35, vcc
	v_lshlrev_b64 v[2:3], 12, v[2:3]
	v_mov_b32_e32 v37, s0
	v_cndmask_b32_e32 v4, v36, v37, vcc
	v_lshl_add_u64 v[2:3], v[4:5], 0, v[2:3]
	v_lshlrev_b32_e32 v0, 2, v52
	v_lshl_add_u64 v[2:3], v[2:3], 0, v[0:1]
	global_load_dwordx4 v[30:33], v[2:3], off nt
	global_load_dwordx4 v[26:29], v[2:3], off offset:1024 nt
	s_waitcnt lgkmcnt(0)
	global_load_dwordx4 v[18:21], v[2:3], off offset:2048 nt
	s_nop 0
	global_load_dwordx4 v[2:5], v[2:3], off offset:3072 nt
	s_nop 0
	global_load_dwordx4 v[80:83], v[54:55], off
	v_lshl_add_u64 v[10:11], s[42:43], 0, v[50:51]
	v_ashrrev_i32_e32 v12, 11, v12
	v_readlane_b32 s0, v253, 41
	v_mov_b64_e32 v[6:7], s[36:37]
	v_lshl_add_u64 v[70:71], s[42:43], 0, v[10:11]
	v_add_u32_e32 v11, s0, v12
	s_movk_i32 s0, 0x3000
	v_mad_i64_i32 v[6:7], s[0:1], v11, s0, v[6:7]
	s_mov_b64 s[0:1], 0x1000
	s_nop 0
	v_lshl_add_u64 v[92:93], v[6:7], 0, s[0:1]
	v_lshl_add_u64 v[12:13], v[92:93], 0, v[0:1]
	global_load_dwordx4 v[84:87], v[12:13], off
	v_lshl_add_u64 v[94:95], v[6:7], 0, v[0:1]
	global_load_dwordx4 v[88:91], v[94:95], off
	v_mov_b32_e32 v65, v1
	v_mov_b32_e32 v67, v1
	v_mov_b32_e32 v69, v1
	global_load_dwordx4 v[98:101], v[54:55], off offset:1024
	v_lshl_add_u64 v[102:103], v[92:93], 0, v[64:65]
	global_load_dwordx4 v[102:105], v[102:103], off
	global_load_dwordx4 v[106:109], v[94:95], off offset:1024
	global_load_dwordx4 v[110:113], v[54:55], off offset:2048
	v_lshl_add_u64 v[114:115], v[92:93], 0, v[66:67]
	global_load_dwordx4 v[114:117], v[114:115], off
	global_load_dwordx4 v[118:121], v[94:95], off offset:2048
	global_load_dwordx4 v[122:125], v[54:55], off offset:3072
	v_lshl_add_u64 v[126:127], v[92:93], 0, v[68:69]
	global_load_dwordx4 v[126:129], v[126:127], off
	global_load_dwordx4 v[130:133], v[94:95], off offset:3072
	s_movk_i32 s2, 0x4800
	v_cmp_gt_i32_e64 s[4:5], s2, v10
	v_cmp_gt_i32_e32 vcc, s2, v70
	s_nop 1
	v_cndmask_b32_e64 v168, v50, v10, s[4:5]
	v_cndmask_b32_e32 v169, v50, v70, vcc
	v_cmp_gt_i32_e64 s[4:5], s3, v168
	v_cmp_gt_i32_e32 vcc, s3, v169
	v_ashrrev_i32_e32 v171, 31, v168
	v_add_u32_e32 v170, 0xffffc000, v168
	v_ashrrev_i32_e32 v175, 31, v169
	v_add_u32_e32 v174, 0xffffc000, v169
	v_cndmask_b32_e64 v171, 0, v171, s[4:5]
	v_cndmask_b32_e64 v170, v170, v168, s[4:5]
	v_cndmask_b32_e64 v173, v34, v35, s[4:5]
	v_cndmask_b32_e64 v172, v36, v37, s[4:5]
	v_cndmask_b32_e32 v175, 0, v175, vcc
	v_cndmask_b32_e32 v174, v174, v169, vcc
	v_cndmask_b32_e32 v177, v34, v35, vcc
	v_cndmask_b32_e32 v176, v36, v37, vcc
	v_lshlrev_b64 v[170:171], 12, v[170:171]
	v_lshlrev_b64 v[174:175], 12, v[174:175]
	v_lshl_add_u64 v[170:171], v[172:173], 0, v[170:171]
	v_lshl_add_u64 v[174:175], v[176:177], 0, v[174:175]
	v_lshl_add_u64 v[170:171], v[170:171], 0, v[0:1]
	v_lshl_add_u64 v[174:175], v[174:175], 0, v[0:1]
	global_load_dwordx4 v[134:137], v[170:171], off nt
	global_load_dwordx4 v[138:141], v[170:171], off offset:1024 nt
	global_load_dwordx4 v[142:145], v[170:171], off offset:2048 nt
	global_load_dwordx4 v[146:149], v[170:171], off offset:3072 nt
	global_load_dwordx4 v[150:153], v[174:175], off nt
	global_load_dwordx4 v[154:157], v[174:175], off offset:1024 nt
	global_load_dwordx4 v[158:161], v[174:175], off offset:2048 nt
	global_load_dwordx4 v[164:167], v[174:175], off offset:3072 nt
	v_lshl_add_u64 v[8:9], v[62:63], 0, v[58:59]
	s_mov_b32 s0, 0x133c000
	v_add_co_u32_e32 v72, vcc, s0, v8
	s_movk_i32 s2, 0x4800
	s_nop 0
	v_addc_co_u32_e32 v73, vcc, 0, v9, vcc
	v_cmp_gt_i32_e64 s[0:1], s2, v10
	v_cmp_gt_i32_e32 vcc, s2, v70
	v_mov_b32_e32 v65, v1
	v_cndmask_b32_e64 v38, v50, v10, s[0:1]
	v_ashrrev_i32_e32 v39, 31, v38
	v_add_u32_e32 v40, 0xffffc000, v38
	v_cmp_gt_i32_e64 s[4:5], s3, v38
	s_waitcnt vmcnt(14)
	v_mov_b32_e32 v8, v31
	s_waitcnt vmcnt(13)
	v_mov_b32_e32 v9, v27
	v_mov_b32_e32 v6, v30
	v_mov_b32_e32 v7, v26
	s_waitcnt vmcnt(12)
	v_mov_b32_e32 v14, v19
	s_waitcnt vmcnt(11)
	v_mov_b32_e32 v15, v3
	v_pk_mul_f32 v[8:9], v[8:9], v[8:9]
	v_mov_b32_e32 v10, v32
	v_mov_b32_e32 v11, v28
	v_mov_b32_e32 v12, v18
	v_mov_b32_e32 v13, v2
	v_pk_mul_f32 v[14:15], v[14:15], v[14:15]
	v_pk_fma_f32 v[6:7], v[6:7], v[6:7], v[8:9]
	v_mov_b32_e32 v16, v33
	v_mov_b32_e32 v17, v29
	v_mov_b32_e32 v22, v20
	v_mov_b32_e32 v23, v4
	v_pk_fma_f32 v[8:9], v[12:13], v[12:13], v[14:15]
	v_pk_fma_f32 v[6:7], v[10:11], v[10:11], v[6:7]
	v_mov_b32_e32 v24, v21
	v_mov_b32_e32 v25, v5
	v_pk_fma_f32 v[8:9], v[22:23], v[22:23], v[8:9]
	v_pk_fma_f32 v[6:7], v[16:17], v[16:17], v[6:7]
	v_pk_fma_f32 v[8:9], v[24:25], v[24:25], v[8:9]
	v_add_f32_e32 v6, v6, v7
	v_add_f32_e32 v6, v6, v8
	v_add_f32_e32 v8, v6, v9
	v_mov_b32_e32 v9, v8
	s_nop 1
	v_permlane32_swap_b32_e32 v8, v9
	v_cndmask_b32_e32 v10, v50, v70, vcc
	v_cndmask_b32_e64 v7, 0, v39, s[4:5]
	v_cndmask_b32_e64 v6, v40, v38, s[4:5]
	v_add_u32_e32 v14, 0xffffc000, v10
	s_waitcnt lgkmcnt(0)
	v_add_f32_e32 v11, v8, v9
	v_mov_b32_e32 v12, v11
	s_nop 1
	v_permlane16_swap_b32_e32 v11, v12
	v_cndmask_b32_e64 v9, v34, v35, s[4:5]
	v_cndmask_b32_e64 v8, v36, v37, s[4:5]
	v_cmp_gt_i32_e64 s[4:5], s3, v10
	v_ashrrev_i32_e32 v13, 31, v10
	s_waitcnt lgkmcnt(0)
	v_add_f32_e32 v15, v11, v12
	s_nop 1
	v_mov_b32_dpp v16, v15 row_ror:8 row_mask:0xf bank_mask:0xf
	v_cndmask_b32_e64 v10, v14, v10, s[4:5]
	v_cndmask_b32_e64 v11, 0, v13, s[4:5]
	v_lshlrev_b64 v[6:7], 12, v[6:7]
	v_lshl_add_u64 v[6:7], v[8:9], 0, v[6:7]
	s_waitcnt lgkmcnt(0)
	v_add_f32_e32 v14, v15, v16
	s_nop 1
	v_mov_b32_dpp v15, v14 row_ror:4 row_mask:0xf bank_mask:0xf
	v_lshlrev_b64 v[8:9], 12, v[10:11]
	v_cndmask_b32_e64 v13, v34, v35, s[4:5]
	v_cndmask_b32_e64 v12, v36, v37, s[4:5]
	v_lshl_add_u64 v[8:9], v[12:13], 0, v[8:9]
	s_waitcnt lgkmcnt(0)
	v_add_f32_e32 v10, v14, v15
	s_nop 1
	v_mov_b32_dpp v11, v10 quad_perm:[2,3,0,1] row_mask:0xf bank_mask:0xf
	v_lshl_add_u64 v[6:7], v[6:7], 0, v[0:1]
	v_lshl_add_u64 v[8:9], v[8:9], 0, v[0:1]
	s_waitcnt vmcnt(0)
	v_mov_b64_e32 v[46:47], v[134:135]
	v_mov_b64_e32 v[48:49], v[136:137]
	v_mov_b64_e32 v[42:43], v[138:139]
	v_mov_b64_e32 v[44:45], v[140:141]
	v_mov_b64_e32 v[38:39], v[142:143]
	v_mov_b64_e32 v[40:41], v[144:145]
	v_mov_b64_e32 v[34:35], v[146:147]
	v_mov_b64_e32 v[36:37], v[148:149]
	v_mov_b64_e32 v[22:23], v[150:151]
	v_mov_b64_e32 v[24:25], v[152:153]
	v_mov_b64_e32 v[14:15], v[154:155]
	v_mov_b64_e32 v[16:17], v[156:157]
	s_waitcnt lgkmcnt(0)
	v_add_f32_e32 v10, v10, v11
	s_nop 1
	v_mov_b32_dpp v11, v10 quad_perm:[1,0,3,2] row_mask:0xf bank_mask:0xf
	s_waitcnt vmcnt(7)
	v_pk_add_f32 v[84:85], v[84:85], 1.0 op_sel_hi:[1,0]
	v_pk_add_f32 v[86:87], v[86:87], 1.0 op_sel_hi:[1,0]
	s_waitcnt lgkmcnt(0)
	v_add_f32_e32 v6, v10, v11
	v_fmamk_f32 v6, v6, 0x3a800000, v196
	v_mul_f32_e32 v7, 0x4b800000, v6
	v_cmp_gt_f32_e64 s[4:5], s33, v6
	s_waitcnt vmcnt(1)
	v_mul_f32_e32 v71, v23, v23
	v_cndmask_b32_e64 v6, v6, v7, s[4:5]
	v_rsq_f32_e32 v67, v6
	v_mov_b64_e32 v[10:11], v[158:159]
	v_mov_b64_e32 v[12:13], v[160:161]
	v_mov_b64_e32 v[6:7], v[164:165]
	v_mov_b64_e32 v[8:9], v[166:167]
	s_waitcnt vmcnt(2)
	v_mul_f32_e32 v79, v15, v15
	v_fmac_f32_e32 v71, v22, v22
	v_mul_f32_e32 v69, 0x45800000, v67
	v_cndmask_b32_e64 v96, v67, v69, s[4:5]
	v_pk_mul_f32 v[30:31], v[30:31], v[96:97] op_sel_hi:[1,0]
	v_pk_mul_f32 v[32:33], v[32:33], v[96:97] op_sel_hi:[1,0]
	v_pk_mul_f32 v[30:31], v[30:31], v[80:81]
	v_pk_mul_f32 v[32:33], v[32:33], v[82:83]
	v_pk_fma_f32 v[30:31], v[30:31], v[84:85], v[88:89]
	v_pk_fma_f32 v[32:33], v[32:33], v[86:87], v[90:91]
	v_cvt_pk_bf16_f32 v30, v30, v31
	v_cvt_pk_bf16_f32 v31, v32, v33
	global_store_dwordx2 v[72:73], v[30:31], off
	s_nop 0
	v_pk_mul_f32 v[26:27], v[26:27], v[96:97] op_sel_hi:[1,0]
	v_pk_mul_f32 v[28:29], v[28:29], v[96:97] op_sel_hi:[1,0]
	v_mov_b32_e32 v67, v1
	v_pk_mul_f32 v[18:19], v[18:19], v[96:97] op_sel_hi:[1,0]
	v_pk_mul_f32 v[20:21], v[20:21], v[96:97] op_sel_hi:[1,0]
	v_mov_b32_e32 v69, v1
	v_fmac_f32_e32 v79, v14, v14
	v_fmac_f32_e32 v71, v24, v24
	v_fmac_f32_e32 v79, v16, v16
	v_fmac_f32_e32 v71, v25, v25
	v_fmac_f32_e32 v79, v17, v17
	v_pk_mul_f32 v[2:3], v[2:3], v[96:97] op_sel_hi:[1,0]
	v_pk_mul_f32 v[4:5], v[4:5], v[96:97] op_sel_hi:[1,0]
	s_waitcnt vmcnt(2)
	v_pk_mul_f32 v[26:27], v[26:27], v[98:99]
	v_pk_mul_f32 v[28:29], v[28:29], v[100:101]
	s_waitcnt vmcnt(1)
	v_pk_add_f32 v[30:31], v[102:103], 1.0 op_sel_hi:[1,0]
	v_pk_add_f32 v[32:33], v[104:105], 1.0 op_sel_hi:[1,0]
	s_waitcnt vmcnt(0)
	v_pk_fma_f32 v[26:27], v[26:27], v[30:31], v[106:107]
	v_pk_fma_f32 v[28:29], v[28:29], v[32:33], v[108:109]
	v_cvt_pk_bf16_f32 v26, v26, v27
	v_cvt_pk_bf16_f32 v27, v28, v29
	global_store_dwordx2 v[72:73], v[26:27], off offset:512
	s_nop 0
	s_waitcnt vmcnt(2)
	v_pk_mul_f32 v[18:19], v[18:19], v[110:111]
	v_pk_mul_f32 v[20:21], v[20:21], v[112:113]
	s_waitcnt vmcnt(1)
	v_pk_add_f32 v[26:27], v[114:115], 1.0 op_sel_hi:[1,0]
	v_pk_add_f32 v[28:29], v[116:117], 1.0 op_sel_hi:[1,0]
	s_waitcnt vmcnt(0)
	v_pk_fma_f32 v[18:19], v[18:19], v[26:27], v[118:119]
	v_pk_fma_f32 v[20:21], v[20:21], v[28:29], v[120:121]
	v_cvt_pk_bf16_f32 v18, v18, v19
	v_cvt_pk_bf16_f32 v19, v20, v21
	global_store_dwordx2 v[72:73], v[18:19], off offset:1024
	v_mul_f32_e32 v18, v47, v47
	v_mul_f32_e32 v19, v43, v43
	v_mul_f32_e32 v20, v39, v39
	v_fmac_f32_e32 v18, v46, v46
	v_fmac_f32_e32 v19, v42, v42
	v_mul_f32_e32 v84, v11, v11
	v_mul_f32_e32 v21, v35, v35
	v_fmac_f32_e32 v20, v38, v38
	v_mul_f32_e32 v85, v7, v7
	v_fmac_f32_e32 v18, v48, v48
	v_fmac_f32_e32 v19, v44, v44
	v_fmac_f32_e32 v84, v10, v10
	v_fmac_f32_e32 v21, v34, v34
	v_fmac_f32_e32 v20, v40, v40
	v_fmac_f32_e32 v85, v6, v6
	v_fmac_f32_e32 v18, v49, v49
	v_fmac_f32_e32 v19, v45, v45
	v_fmac_f32_e32 v84, v12, v12
	v_fmac_f32_e32 v21, v36, v36
	v_fmac_f32_e32 v20, v41, v41
	v_fmac_f32_e32 v85, v8, v8
	v_add_f32_e32 v18, v18, v19
	v_fmac_f32_e32 v84, v13, v13
	v_add_f32_e32 v19, v71, v79
	v_fmac_f32_e32 v21, v37, v37
	v_fmac_f32_e32 v85, v9, v9
	v_add_f32_e32 v18, v18, v20
	v_add_f32_e32 v19, v19, v84
	v_add_f32_e32 v18, v18, v21
	v_add_f32_e32 v19, v19, v85
	v_mov_b32_e32 v20, v18
	s_nop 1
	v_permlane32_swap_b32_e32 v18, v20
	v_mov_b32_e32 v21, v19
	s_nop 1
	v_permlane32_swap_b32_e32 v19, v21
	s_waitcnt lgkmcnt(1)
	v_add_f32_e32 v18, v18, v20
	s_waitcnt lgkmcnt(0)
	v_add_f32_e32 v19, v19, v21
	v_mov_b32_e32 v20, v18
	s_nop 1
	v_permlane16_swap_b32_e32 v18, v20
	v_mov_b32_e32 v21, v19
	s_nop 1
	v_permlane16_swap_b32_e32 v19, v21
	s_waitcnt lgkmcnt(1)
	v_add_f32_e32 v18, v18, v20
	s_waitcnt lgkmcnt(0)
	v_add_f32_e32 v19, v19, v21
	v_mov_b32_dpp v20, v18 row_ror:8 row_mask:0xf bank_mask:0xf
	s_nop 0
	v_mov_b32_dpp v21, v19 row_ror:8 row_mask:0xf bank_mask:0xf
	s_waitcnt lgkmcnt(1)
	v_add_f32_e32 v18, v18, v20
	s_waitcnt lgkmcnt(0)
	v_add_f32_e32 v19, v19, v21
	v_mov_b32_dpp v20, v18 row_ror:4 row_mask:0xf bank_mask:0xf
	s_nop 0
	v_mov_b32_dpp v21, v19 row_ror:4 row_mask:0xf bank_mask:0xf
	s_waitcnt lgkmcnt(1)
	v_add_f32_e32 v18, v18, v20
	s_waitcnt lgkmcnt(0)
	v_add_f32_e32 v19, v19, v21
	v_mov_b32_dpp v20, v18 quad_perm:[2,3,0,1] row_mask:0xf bank_mask:0xf
	s_nop 0
	v_mov_b32_dpp v21, v19 quad_perm:[2,3,0,1] row_mask:0xf bank_mask:0xf
	s_waitcnt lgkmcnt(1)
	v_add_f32_e32 v20, v18, v20
	s_waitcnt lgkmcnt(0)
	v_add_f32_e32 v18, v19, v21
	v_mov_b32_dpp v21, v20 quad_perm:[1,0,3,2] row_mask:0xf bank_mask:0xf
	s_nop 0
	v_mov_b32_dpp v19, v18 quad_perm:[1,0,3,2] row_mask:0xf bank_mask:0xf
	s_waitcnt vmcnt(2)
	v_pk_mul_f32 v[2:3], v[2:3], v[122:123]
	v_pk_mul_f32 v[4:5], v[4:5], v[124:125]
	s_waitcnt vmcnt(1)
	v_pk_add_f32 v[26:27], v[126:127], 1.0 op_sel_hi:[1,0]
	v_pk_add_f32 v[28:29], v[128:129], 1.0 op_sel_hi:[1,0]
	s_waitcnt vmcnt(0)
	v_pk_fma_f32 v[2:3], v[2:3], v[26:27], v[130:131]
	v_pk_fma_f32 v[4:5], v[4:5], v[28:29], v[132:133]
	v_cvt_pk_bf16_f32 v2, v2, v3
	v_cvt_pk_bf16_f32 v3, v4, v5
	global_store_dwordx2 v[72:73], v[2:3], off offset:1536
	s_and_saveexec_b64 s[12:13], s[0:1]
	s_cbranch_execz .LBB0_182
	v_add_u32_e32 v2, s42, v50
	v_min_i32_e32 v2, 0x4000, v2
	v_ashrrev_i32_e32 v2, 11, v2
	v_readlane_b32 s0, v253, 41
	s_waitcnt lgkmcnt(1)
	v_add_f32_e32 v71, v20, v21
	v_fmamk_f32 v71, v71, 0x3a800000, v196
	v_add_u32_e32 v4, s0, v2
	v_mov_b64_e32 v[2:3], s[36:37]
	s_movk_i32 s0, 0x3000
	v_mad_i64_i32 v[30:31], s[0:1], v4, s0, v[2:3]
	s_mov_b64 s[0:1], 0x1000
	s_nop 0
	v_lshl_add_u64 v[72:73], v[30:31], 0, s[0:1]
	v_lshl_add_u64 v[26:27], v[72:73], 0, v[0:1]
	global_load_dwordx4 v[2:5], v[54:55], off
	v_lshl_add_u64 v[80:81], v[30:31], 0, v[0:1]
	global_load_dwordx4 v[26:29], v[26:27], off
	v_mul_f32_e32 v79, 0x4b800000, v71
	global_load_dwordx4 v[30:33], v[80:81], off
	v_mov_b32_e32 v65, v1
	v_mov_b32_e32 v67, v1
	v_mov_b32_e32 v69, v1
	global_load_dwordx4 v[98:101], v[54:55], off offset:1024
	v_lshl_add_u64 v[102:103], v[72:73], 0, v[64:65]
	global_load_dwordx4 v[102:105], v[102:103], off
	global_load_dwordx4 v[106:109], v[80:81], off offset:1024
	global_load_dwordx4 v[110:113], v[54:55], off offset:2048
	v_lshl_add_u64 v[114:115], v[72:73], 0, v[66:67]
	global_load_dwordx4 v[114:117], v[114:115], off
	global_load_dwordx4 v[118:121], v[80:81], off offset:2048
	global_load_dwordx4 v[122:125], v[54:55], off offset:3072
	v_lshl_add_u64 v[126:127], v[72:73], 0, v[68:69]
	global_load_dwordx4 v[126:129], v[126:127], off
	global_load_dwordx4 v[130:133], v[80:81], off offset:3072
	v_cmp_gt_f32_e64 s[0:1], s33, v71
	v_lshl_add_u64 v[20:21], v[60:61], 0, v[58:59]
	v_cndmask_b32_e64 v71, v71, v79, s[0:1]
	v_rsq_f32_e32 v71, v71
	s_mov_b32 s2, 0x133c000
	v_add_co_u32_e64 v20, s[4:5], s2, v20
	v_mul_f32_e32 v65, 0x45800000, v71
	v_cndmask_b32_e64 v84, v71, v65, s[0:1]
	v_pk_mul_f32 v[46:47], v[46:47], v[84:85] op_sel_hi:[1,0]
	v_pk_mul_f32 v[48:49], v[48:49], v[84:85] op_sel_hi:[1,0]
	v_addc_co_u32_e64 v21, s[4:5], 0, v21, s[4:5]
	v_pk_mul_f32 v[42:43], v[42:43], v[84:85] op_sel_hi:[1,0]
	v_pk_mul_f32 v[44:45], v[44:45], v[84:85] op_sel_hi:[1,0]
	v_pk_mul_f32 v[38:39], v[38:39], v[84:85] op_sel_hi:[1,0]
	v_pk_mul_f32 v[40:41], v[40:41], v[84:85] op_sel_hi:[1,0]
	v_pk_mul_f32 v[34:35], v[34:35], v[84:85] op_sel_hi:[1,0]
	v_pk_mul_f32 v[36:37], v[36:37], v[84:85] op_sel_hi:[1,0]
	s_waitcnt vmcnt(2)
	v_pk_mul_f32 v[2:3], v[46:47], v[2:3]
	v_pk_mul_f32 v[4:5], v[48:49], v[4:5]
	s_waitcnt vmcnt(1)
	v_pk_add_f32 v[26:27], v[26:27], 1.0 op_sel_hi:[1,0]
	v_pk_add_f32 v[28:29], v[28:29], 1.0 op_sel_hi:[1,0]
	s_waitcnt vmcnt(0)
	v_pk_fma_f32 v[2:3], v[2:3], v[26:27], v[30:31]
	v_pk_fma_f32 v[4:5], v[4:5], v[28:29], v[32:33]
	v_cvt_pk_bf16_f32 v2, v2, v3
	v_cvt_pk_bf16_f32 v3, v4, v5
	global_store_dwordx2 v[20:21], v[2:3], off
	s_nop 0
	s_waitcnt vmcnt(2)
	v_pk_mul_f32 v[2:3], v[42:43], v[98:99]
	s_waitcnt vmcnt(1)
	v_pk_add_f32 v[26:27], v[102:103], 1.0 op_sel_hi:[1,0]
	v_pk_mul_f32 v[4:5], v[44:45], v[100:101]
	v_pk_add_f32 v[28:29], v[104:105], 1.0 op_sel_hi:[1,0]
	s_waitcnt vmcnt(0)
	v_pk_fma_f32 v[2:3], v[2:3], v[26:27], v[106:107]
	v_pk_fma_f32 v[4:5], v[4:5], v[28:29], v[108:109]
	v_cvt_pk_bf16_f32 v2, v2, v3
	v_cvt_pk_bf16_f32 v3, v4, v5
	global_store_dwordx2 v[20:21], v[2:3], off offset:512
	s_nop 0
	s_waitcnt vmcnt(2)
	v_pk_mul_f32 v[2:3], v[38:39], v[110:111]
	s_waitcnt vmcnt(1)
	v_pk_add_f32 v[26:27], v[114:115], 1.0 op_sel_hi:[1,0]
	v_pk_mul_f32 v[4:5], v[40:41], v[112:113]
	v_pk_add_f32 v[28:29], v[116:117], 1.0 op_sel_hi:[1,0]
	s_waitcnt vmcnt(0)
	v_pk_fma_f32 v[2:3], v[2:3], v[26:27], v[118:119]
	v_pk_fma_f32 v[4:5], v[4:5], v[28:29], v[120:121]
	v_cvt_pk_bf16_f32 v2, v2, v3
	v_cvt_pk_bf16_f32 v3, v4, v5
	global_store_dwordx2 v[20:21], v[2:3], off offset:1024
	s_nop 0
	s_waitcnt vmcnt(2)
	v_pk_mul_f32 v[2:3], v[34:35], v[122:123]
	s_waitcnt vmcnt(1)
	v_pk_add_f32 v[26:27], v[126:127], 1.0 op_sel_hi:[1,0]
	v_pk_mul_f32 v[4:5], v[36:37], v[124:125]
	v_pk_add_f32 v[28:29], v[128:129], 1.0 op_sel_hi:[1,0]
	s_waitcnt vmcnt(0)
	v_pk_fma_f32 v[2:3], v[2:3], v[26:27], v[130:131]
	v_pk_fma_f32 v[4:5], v[4:5], v[28:29], v[132:133]
	v_cvt_pk_bf16_f32 v2, v2, v3
	v_cvt_pk_bf16_f32 v3, v4, v5
	global_store_dwordx2 v[20:21], v[2:3], off offset:1536
